# n3 max-reduce via permlane swaps, static prio for waves 4-7 in n3, x1-ssm_b-x3 and n2-n3 fused with block-level barriers (task maps aligned), n2 K/V staging loads batched
# speedup vs baseline: 1.0461x; 1.0066x over previous
.LBB0_47:
	s_nop 0
	v_readlane_b32 s2, v255, 3
	s_cmp_lt_i32 s2, 6
	s_mov_b64 s[2:3], 0
	v_writelane_b32 v255, s2, 4
	s_mov_b64 s[0:1], -1
	s_mov_b64 s[4:5], 0
	v_writelane_b32 v255, s3, 5
	s_cbranch_scc1 .LBB0_143
	v_readlane_b32 s0, v255, 3
	v_writelane_b32 v255, s18, 6
	s_cmp_gt_i32 s0, 9
	s_nop 0
	v_writelane_b32 v255, s19, 7
	s_cbranch_scc0 .LBB0_140
	s_cmp_gt_i32 s0, 10
	s_cbranch_scc0 .LBB0_287
	v_writelane_b32 v255, s74, 8
	s_cmp_gt_i32 s0, 11
	s_nop 0
	v_writelane_b32 v255, s75, 9
	s_cbranch_scc0 .LBB0_290
	s_cmp_eq_u32 s0, 12
	s_mov_b64 s[0:1], -1
	v_writelane_b32 v255, s0, 4
	s_nop 1
	v_writelane_b32 v255, s1, 5
	s_cbranch_scc0 .LBB0_386
	v_mov_b32_e32 v0, v1
	s_cmpk_gt_i32 s61, 0x1ff
	v_mbcnt_lo_u32_b32 v0, -1, v0
	v_mbcnt_hi_u32_b32 v2, -1, v0
	v_add_u32_e32 v0, s67, v2
	v_ashrrev_i32_e32 v0, 6, v0
	s_movk_i32 s57, 0x800
	v_readfirstlane_b32 s8, v0
	s_mov_b32 s60, 0xf149f2ca
	s_cbranch_scc1 .LBB0_385
	s_cmp_lt_u32 s67, 0x100
	s_cbranch_scc1 .Lmy_n3_prio_skip
	s_setprio 1
.Lmy_n3_prio_skip:
	v_bfe_u32 v4, v2, 4, 2
	v_lshlrev_b32_e32 v6, 2, v0
	v_or_b32_e32 v7, v6, v4
	v_bitop3_b32 v6, v6, v2, v4 bitop3:0x36
	s_movk_i32 s6, 0xc00
	v_mul_lo_u32 v7, v7, s6
	v_lshlrev_b32_e32 v6, 3, v6
	s_movk_i32 s7, 0x78
	s_load_dwordx2 s[0:1], s[74:75], 0xf0
	v_bfe_u32 v5, v2, 3, 3
	v_and_or_b32 v6, v6, s7, v7
	v_lshlrev_b32_e32 v136, 3, v0
	v_lshlrev_b32_e32 v121, 1, v6
	v_or_b32_e32 v6, v136, v5
	v_lshrrev_b32_e32 v7, 1, v6
	v_xor_b32_e32 v7, v7, v2
	v_lshlrev_b32_e32 v6, 13, v6
	v_lshlrev_b32_e32 v7, 4, v7
	s_movk_i32 s9, 0x70
	s_waitcnt lgkmcnt(0)
	s_add_u32 s23, s0, 0x16c00000
	v_and_or_b32 v137, v7, s9, v6
	v_add_u32_e32 v6, 8, v0
	s_addc_u32 s24, s1, 0
	v_lshl_or_b32 v5, v6, 3, v5
	s_add_u32 s2, s0, 0x22c00000
	v_lshlrev_b32_e32 v7, 2, v6
	v_lshrrev_b32_e32 v6, 1, v5
	s_addc_u32 s3, s1, 0
	v_xor_b32_e32 v6, v6, v2
	s_add_u32 s4, s0, 0x2ec00000
	v_lshlrev_b32_e32 v5, 13, v5
	v_lshlrev_b32_e32 v6, 4, v6
	s_addc_u32 s5, s1, 0
	v_or_b32_e32 v8, v7, v4
	v_bitop3_b32 v7, v7, v2, v4 bitop3:0x36
	v_and_or_b32 v139, v6, s9, v5
	v_and_b32_e32 v5, 15, v2
	v_bitop3_b32 v6, v4, v2, 15 bitop3:0x78
	v_mul_lo_u32 v8, v8, s6
	v_lshlrev_b32_e32 v7, 3, v7
	s_add_u32 s6, s0, 0x12c00000
	v_lshlrev_b32_e32 v141, 4, v6
	v_bitop3_b32 v6, v4, v5, 4 bitop3:0x36
	v_and_or_b32 v7, v7, s7, v8
	s_addc_u32 s7, s1, 0
	v_lshlrev_b32_e32 v142, 4, v6
	v_bitop3_b32 v6, v4, v5, 8 bitop3:0x36
	v_lshlrev_b32_e32 v143, 4, v6
	v_bitop3_b32 v6, v4, v5, 12 bitop3:0x36
	s_add_u32 s25, s0, 0xaa00000
	v_lshlrev_b32_e32 v138, 1, v7
	v_lshlrev_b32_e32 v153, 4, v6
	s_addc_u32 s26, s1, 0
	v_bfe_u32 v6, v2, 5, 1
	v_lshlrev_b32_e32 v7, 7, v5
	v_lshrrev_b32_e32 v8, 1, v2
	v_bfe_u32 v9, v2, 1, 3
	v_and_or_b32 v154, v8, 8, v7
	v_bitop3_b32 v7, v6, v8, 7 bitop3:0x78
	s_add_u32 s27, s0, 0x1cc00000
	v_lshlrev_b32_e32 v155, 4, v7
	v_bitop3_b32 v7, v6, v9, 2 bitop3:0x36
	s_addc_u32 s28, s1, 0
	s_lshl_b32 s29, s8, 10
	s_movk_i32 s8, 0x2200
	v_and_b32_e32 v3, 63, v2
	v_lshlrev_b32_e32 v156, 4, v7
	v_bitop3_b32 v7, v6, v9, 4 bitop3:0x36
	v_bitop3_b32 v6, v6, v9, 6 bitop3:0x36
	v_mul_lo_u32 v0, v0, s8
	v_readlane_b32 s8, v254, 51
	v_lshlrev_b32_e32 v157, 4, v7
	v_lshlrev_b32_e32 v158, 4, v6
	v_add_u32_e32 v6, s8, v0
	v_and_b32_e32 v7, 48, v2
	v_lshlrev_b32_e32 v0, 4, v5
	v_bfe_u32 v159, v2, 2, 2
	v_and_b32_e32 v160, 3, v2
	v_lshlrev_b32_e32 v2, 2, v3
	v_lshlrev_b32_e32 v140, 8, v5
	v_add_u32_e32 v8, v6, v0
	s_add_i32 s29, s29, 16
	v_mad_u32_u24 v5, v5, s70, v6
	v_lshlrev_b32_e32 v100, 2, v4
	v_xor_b32_e32 v161, 64, v2
	v_xor_b32_e32 v162, 0x80, v2
	v_lshlrev_b32_e32 v6, 7, v4
	v_lshl_add_u64 v[2:3], s[0:1], 0, v[0:1]
	s_mov_b64 s[0:1], 0x1ec00000
	v_mul_u32_u24_e32 v0, 0x110, v4
	s_add_i32 s30, s29, 0x2000
	s_add_i32 s31, s29, 0x8000
	s_add_i32 s34, s29, 0xa000
	v_lshl_add_u64 v[102:103], v[2:3], 0, s[0:1]
	v_lshlrev_b32_e32 v163, 1, v6
	v_lshlrev_b32_e32 v104, 1, v100
	v_mov_b32_e32 v105, v1
	v_add_u32_e32 v164, v8, v0
	v_add_u32_e32 v165, v5, v7
	s_branch .LBB0_55

.LBB0_55:
	s_ashr_i32 s0, s61, 5
	s_and_b32 s35, s61, 31
	s_cmp_lg_u32 s66, 0x100
	s_cbranch_scc1 .Lmy_n3_nomap
	s_bfe_u32 s0, s61, 0x40004
	s_and_b32 s35, s61, 15
	s_lshl_b32 s35, s35, 1
	s_lshr_b32 s1, s61, 8
	s_or_b32 s35, s35, s1
.Lmy_n3_nomap:
	s_ashr_i32 s10, s0, 2
	s_ashr_i32 s1, s0, 31
	s_and_b32 s11, s0, 3
	s_xor_b32 s36, s35, 63
	s_lshl_b32 s37, s10, 12
	s_lshl_b64 s[0:1], s[0:1], 15
	s_add_u32 s8, s25, s0
	s_addc_u32 s9, s26, s1
	s_mul_i32 s1, s10, 0x1800000
	v_lshl_or_b32 v2, s11, 2, v160
	s_mul_hi_i32 s0, s10, 0x1800000
	s_add_u32 s1, s23, s1
	s_addc_u32 s0, s24, s0
	s_lshl_b32 s12, s11, 8
	v_lshlrev_b32_e32 v0, 2, v2
	s_add_u32 s40, s1, s12
	v_lshl_add_u64 v[106:107], s[4:5], 0, v[0:1]
	v_lshlrev_b32_e32 v0, 8, v2
	s_addc_u32 s41, s0, 0
	s_lshl_b32 s0, s10, 2
	v_lshl_add_u64 v[2:3], s[6:7], 0, v[0:1]
	v_lshl_or_b32 v4, s11, 10, v163
	v_mov_b32_e32 v5, v1
	s_or_b32 s42, s0, s11
	v_lshl_add_u64 v[108:109], v[102:103], 0, v[4:5]
	v_lshl_add_u64 v[110:111], s[2:3], 0, v[0:1]
	v_lshl_add_u64 v[112:113], v[2:3], 0, v[104:105]
	s_mov_b64 s[0:1], -1
	s_branch .LBB0_57

.LBB0_64:
	s_andn2_b64 vcc, exec, s[20:21]
	s_cbranch_vccnz .LBB0_66
	v_max3_f32 v0, v96, s60, v97
	v_max3_f32 v0, v0, v98, v99
	v_max3_f32 v0, v0, v92, v93
	v_max3_f32 v0, v0, v94, v95
	v_max3_f32 v0, v0, v88, v89
	v_max3_f32 v0, v0, v90, v91
	v_max3_f32 v0, v0, v84, v85
	v_max3_f32 v0, v0, v86, v87
	v_cndmask_b32_e64 v0, v146, v0, s[38:39]
	v_mov_b32_e32 v2, v0
	s_waitcnt lgkmcnt(0)
	s_nop 1
	v_permlane16_swap_b32_e32 v2, v0
	v_max_f32_e32 v2, v2, v2
	v_max_f32_e32 v0, v0, v2
	v_mov_b32_e32 v2, v0
	s_nop 1
	v_permlane32_swap_b32_e32 v2, v0
	v_max3_f32 v3, v217, v0, v2
	v_cndmask_b32_e64 v148, v147, v3, s[38:39]
	v_sub_f32_e32 v2, v96, v148
	v_sub_f32_e32 v96, v97, v148
	v_exp_f32_e32 v2, v2
	v_sub_f32_e32 v97, v98, v148
	v_exp_f32_e32 v218, v96
	v_sub_f32_e32 v98, v99, v148
	v_exp_f32_e32 v219, v97
	v_sub_f32_e32 v92, v92, v148
	v_exp_f32_e32 v220, v98
	v_sub_f32_e32 v93, v93, v148
	v_exp_f32_e32 v221, v92
	v_add_f32_e32 v92, 0, v2
	v_add_f32_e32 v92, v218, v92
	v_exp_f32_e32 v222, v93
	v_sub_f32_e32 v93, v94, v148
	v_add_f32_e32 v92, v219, v92
	v_exp_f32_e32 v223, v93
	v_sub_f32_e32 v93, v95, v148
	v_add_f32_e32 v92, v220, v92
	v_exp_f32_e32 v224, v93
	v_sub_f32_e32 v88, v88, v148
	v_add_f32_e32 v92, v221, v92
	v_exp_f32_e32 v225, v88
	v_sub_f32_e32 v88, v89, v148
	v_add_f32_e32 v92, v222, v92
	v_exp_f32_e32 v226, v88
	v_sub_f32_e32 v88, v90, v148
	v_add_f32_e32 v92, v223, v92
	v_exp_f32_e32 v227, v88
	v_sub_f32_e32 v88, v91, v148
	v_add_f32_e32 v92, v224, v92
	v_exp_f32_e32 v228, v88
	v_sub_f32_e32 v84, v84, v148
	v_add_f32_e32 v88, v225, v92
	v_exp_f32_e32 v229, v84
	v_sub_f32_e32 v84, v85, v148
	v_add_f32_e32 v88, v226, v88
	v_exp_f32_e32 v230, v84
	v_sub_f32_e32 v84, v86, v148
	v_add_f32_e32 v88, v227, v88
	v_exp_f32_e32 v231, v84
	v_sub_f32_e32 v84, v87, v148
	v_sub_f32_e32 v0, v217, v3
	v_add_f32_e32 v88, v228, v88
	v_exp_f32_e32 v232, v84
	v_exp_f32_e32 v0, v0
	v_add_f32_e32 v84, v229, v88
	v_add_f32_e32 v84, v230, v84
	v_add_f32_e32 v84, v231, v84
	v_add_f32_e32 v216, v232, v84

.LBB0_68:
	s_andn2_b64 vcc, exec, s[0:1]
	s_cbranch_vccnz .LBB0_70
	v_max3_f32 v2, v80, s60, v81
	v_max3_f32 v2, v2, v82, v83
	v_max3_f32 v2, v2, v72, v73
	v_max3_f32 v2, v2, v74, v75
	v_max3_f32 v2, v2, v68, v69
	v_max3_f32 v2, v2, v70, v71
	v_max3_f32 v2, v2, v76, v77
	v_max3_f32 v2, v2, v78, v79
	v_cndmask_b32_e64 v2, v146, v2, s[38:39]
	v_mov_b32_e32 v92, v2
	s_waitcnt lgkmcnt(0)
	s_nop 1
	v_permlane16_swap_b32_e32 v92, v2
	v_max_f32_e32 v92, v92, v92
	v_max_f32_e32 v2, v2, v92
	v_mov_b32_e32 v92, v2
	s_nop 1
	v_permlane32_swap_b32_e32 v92, v2
	v_max3_f32 v92, v215, v2, v92
	v_cndmask_b32_e64 v93, v147, v92, s[38:39]
	v_sub_f32_e32 v80, v80, v93
	v_sub_f32_e32 v81, v81, v93
	v_exp_f32_e32 v94, v80
	v_sub_f32_e32 v82, v82, v93
	v_exp_f32_e32 v95, v81
	v_sub_f32_e32 v83, v83, v93
	v_exp_f32_e32 v96, v82
	v_sub_f32_e32 v72, v72, v93
	v_exp_f32_e32 v97, v83
	v_sub_f32_e32 v73, v73, v93
	v_exp_f32_e32 v98, v72
	v_add_f32_e32 v72, 0, v94
	v_add_f32_e32 v72, v95, v72
	v_exp_f32_e32 v99, v73
	v_sub_f32_e32 v73, v74, v93
	v_add_f32_e32 v72, v96, v72
	v_exp_f32_e32 v217, v73
	v_sub_f32_e32 v73, v75, v93
	v_add_f32_e32 v72, v97, v72
	v_exp_f32_e32 v218, v73
	v_sub_f32_e32 v68, v68, v93
	v_add_f32_e32 v72, v98, v72
	v_exp_f32_e32 v219, v68
	v_sub_f32_e32 v68, v69, v93
	v_add_f32_e32 v72, v99, v72
	v_exp_f32_e32 v220, v68
	v_sub_f32_e32 v68, v70, v93
	v_add_f32_e32 v72, v217, v72
	v_exp_f32_e32 v221, v68
	v_sub_f32_e32 v68, v71, v93
	v_add_f32_e32 v72, v218, v72
	v_exp_f32_e32 v222, v68
	v_sub_f32_e32 v69, v76, v93
	v_add_f32_e32 v68, v219, v72
	v_exp_f32_e32 v223, v69
	v_sub_f32_e32 v69, v77, v93
	v_add_f32_e32 v68, v220, v68
	v_exp_f32_e32 v224, v69
	v_sub_f32_e32 v69, v78, v93
	v_add_f32_e32 v68, v221, v68
	v_exp_f32_e32 v225, v69
	v_sub_f32_e32 v69, v79, v93
	v_sub_f32_e32 v2, v215, v92
	v_add_f32_e32 v68, v222, v68
	v_exp_f32_e32 v226, v69
	v_exp_f32_e32 v2, v2
	v_add_f32_e32 v68, v223, v68
	v_add_f32_e32 v68, v224, v68
	v_add_f32_e32 v68, v225, v68
	v_add_f32_e32 v93, v226, v68

.LBB0_292:
	s_andn2_b64 vcc, exec, s[0:1]
	s_cbranch_vccnz .LBB0_299
	s_mov_b32 s0, s61
	v_mov_b32_e32 v0, v1
	s_lshl_b32 s0, s0, 9
	v_mbcnt_lo_u32_b32 v0, -1, v0
	v_mbcnt_hi_u32_b32 v0, -1, v0
	s_add_i32 s0, s0, s67
	v_add_u32_e32 v60, s0, v0
	s_cmp_lg_u32 s66, 0x100
	s_cbranch_scc1 .Lmy_b_noremap
	s_and_b32 s0, s61, 7
	s_lshl_b32 s0, s0, 2
	s_lshr_b32 s2, s61, 6
	s_add_i32 s0, s0, s2
	s_lshl_b32 s0, s0, 3
	s_bfe_u32 s2, s61, 0x30003
	s_or_b32 s0, s0, s2
	s_lshr_b32 s2, s0, 1
	s_and_b32 s0, s0, 1
	s_lshl_b32 s0, s0, 8
	s_add_i32 s0, s0, s2
	s_lshl_b32 s0, s0, 6
	v_add_u32_e32 v2, s67, v0
	v_and_b32_e32 v3, 63, v2
	v_lshrrev_b32_e32 v4, 6, v2
	v_lshl_add_u32 v3, v4, 13, v3
	v_add_u32_e32 v60, s0, v3
	v_cmp_gt_u32_e32 vcc, 0x80, v2
	v_mov_b32_e32 v3, 0x8000
	s_nop 0
	v_cndmask_b32_e32 v60, v3, v60, vcc
.Lmy_b_noremap:
	s_mov_b32 s0, 0x8000
	v_cmp_gt_i32_e32 vcc, s0, v60
	s_and_saveexec_b64 s[0:1], vcc
	s_cbranch_execz .LBB0_298
	s_load_dwordx2 s[4:5], s[74:75], 0xf0
	v_and_b32_e32 v6, 63, v0
	v_lshlrev_b32_e32 v0, 3, v6
	s_mov_b64 s[6:7], 0x26c00000
	s_waitcnt lgkmcnt(0)
	s_add_u32 s2, s4, 0xa140000
	v_lshl_add_u64 v[2:3], s[4:5], 0, v[0:1]
	v_lshlrev_b32_e32 v0, 1, v6
	s_addc_u32 s3, s5, 0
	v_lshl_add_u64 v[4:5], s[4:5], 0, v[0:1]
	s_mov_b64 s[4:5], 0x2c000000
	v_lshl_add_u64 v[2:3], v[2:3], 0, s[6:7]
	v_lshl_add_u64 v[4:5], v[4:5], 0, s[4:5]
	v_lshl_or_b32 v0, s18, 13, v6
	s_mov_b64 s[4:5], 0

.LBB0_385:
	s_setprio 0
	s_mov_b64 s[0:1], 0
	v_writelane_b32 v255, s0, 4
	s_mov_b32 s71, 0x20000
	s_mov_b32 s72, 0x3fb8aa3b
	v_writelane_b32 v255, s1, 5
	s_movk_i32 s73, 0x7fff
	s_mov_b32 s76, 0xbfb8aa3b

.LBB0_390:
	s_lshl_b32 s1, s8, 7
	s_and_b32 s15, s1, 0x780
	s_xor_b32 s20, s15, 0xf80
	s_lshr_b32 s1, s20, 4
	s_add_i32 s1, s1, 22
	s_lshr_b32 s1, s1, 4
	s_min_u32 s6, s1, 16
	s_add_i32 s6, s6, 1
	s_lshl_b32 s1, s6, 8
	s_ashr_i32 s0, s8, 4
	s_and_b32 s7, s1, 0x3e00
	v_cmp_gt_i32_e32 vcc, s7, v91
	s_ashr_i32 s1, s0, 31
	s_barrier
	s_mov_b32 s14, s8
	s_lshl_b64 s[4:5], s[0:1], 16
	v_lshl_add_u64 v[2:3], v[88:89], 0, s[4:5]
	v_ashrrev_i32_e32 v8, 4, v91
	v_mov_b32_e32 v9, 0
	v_lshlrev_b64 v[4:5], 8, v[8:9]
	v_lshl_add_u64 v[4:5], v[2:3], 0, v[4:5]
	v_mad_u32_u24 v0, v8, s70, v90
	s_lshr_b32 s9, s7, 9
	v_readlane_b32 s7, v255, 10
	s_add_u32 s4, s7, s4
	v_readlane_b32 s7, v255, 11
	s_addc_u32 s5, s7, s5
	v_lshrrev_b32_e32 v10, 2, v91
	v_and_b32_e32 v12, 3, v91
	v_lshlrev_b32_e32 v12, 4, v12
	v_lshl_add_u32 v13, v10, 9, v12
	v_mul_u32_u24_e32 v10, 0x210, v10
	s_mov_b32 s12, 0x11010
	v_add3_u32 v11, v10, v12, s12
	s_lshl_b32 s6, s6, 1
	s_and_b32 s8, s6, 0x7c
	s_lshr_b32 s8, s8, 2
	global_load_dwordx4 v[20:23], v[4:5], off
	s_cmp_lt_u32 s9, 2
	s_cbranch_scc1 .Lmy_n2_kld
	s_mov_b64 s[10:11], 0x2000
	v_lshl_add_u64 v[6:7], v[4:5], 0, s[10:11]
	global_load_dwordx4 v[24:27], v[6:7], off
	s_cmp_lt_u32 s9, 3
	s_cbranch_scc1 .Lmy_n2_kld
	s_mov_b64 s[10:11], 0x4000
	v_lshl_add_u64 v[6:7], v[4:5], 0, s[10:11]
	global_load_dwordx4 v[28:31], v[6:7], off
	s_cmp_lt_u32 s9, 4
	s_cbranch_scc1 .Lmy_n2_kld
	s_mov_b64 s[10:11], 0x6000
	v_lshl_add_u64 v[6:7], v[4:5], 0, s[10:11]
	global_load_dwordx4 v[32:35], v[6:7], off
	s_cmp_lt_u32 s9, 5
	s_cbranch_scc1 .Lmy_n2_kld
	s_mov_b64 s[10:11], 0x8000
	v_lshl_add_u64 v[6:7], v[4:5], 0, s[10:11]
	global_load_dwordx4 v[36:39], v[6:7], off
	s_cmp_lt_u32 s9, 6
	s_cbranch_scc1 .Lmy_n2_kld
	s_mov_b64 s[10:11], 0xa000
	v_lshl_add_u64 v[6:7], v[4:5], 0, s[10:11]
	global_load_dwordx4 v[40:43], v[6:7], off
	s_cmp_lt_u32 s9, 7
	s_cbranch_scc1 .Lmy_n2_kld
	s_mov_b64 s[10:11], 0xc000
	v_lshl_add_u64 v[6:7], v[4:5], 0, s[10:11]
	global_load_dwordx4 v[44:47], v[6:7], off
	s_cmp_lt_u32 s9, 8
	s_cbranch_scc1 .Lmy_n2_kld
	s_mov_b64 s[10:11], 0xe000
	v_lshl_add_u64 v[6:7], v[4:5], 0, s[10:11]
	global_load_dwordx4 v[48:51], v[6:7], off
.Lmy_n2_kld:
	global_load_dwordx4 v[52:55], v13, s[4:5]
	s_cmp_lt_u32 s8, 2
	s_cbranch_scc1 .Lmy_n2_vld
	global_load_dwordx4 v[56:59], v13, s[4:5] offset:64
	s_cmp_lt_u32 s8, 3
	s_cbranch_scc1 .Lmy_n2_vld
	global_load_dwordx4 v[60:63], v13, s[4:5] offset:128
	s_cmp_lt_u32 s8, 4
	s_cbranch_scc1 .Lmy_n2_vld
	global_load_dwordx4 v[64:67], v13, s[4:5] offset:192
	s_cmp_lt_u32 s8, 5
	s_cbranch_scc1 .Lmy_n2_vld
	global_load_dwordx4 v[68:71], v13, s[4:5] offset:256
	s_cmp_lt_u32 s8, 6
	s_cbranch_scc1 .Lmy_n2_vld
	global_load_dwordx4 v[72:75], v13, s[4:5] offset:320
	s_cmp_lt_u32 s8, 7
	s_cbranch_scc1 .Lmy_n2_vld
	global_load_dwordx4 v[76:79], v13, s[4:5] offset:384
	s_cmp_lt_u32 s8, 8
	s_cbranch_scc1 .Lmy_n2_vld
	global_load_dwordx4 v[80:83], v13, s[4:5] offset:448
.Lmy_n2_vld:
	s_waitcnt vmcnt(0)
	ds_write_b128 v0, v[20:23]
	s_cmp_lt_u32 s9, 2
	s_cbranch_scc1 .Lmy_n2_kwr
	ds_write_b128 v0, v[24:27] offset:8704
	s_cmp_lt_u32 s9, 3
	s_cbranch_scc1 .Lmy_n2_kwr
	ds_write_b128 v0, v[28:31] offset:17408
	s_cmp_lt_u32 s9, 4
	s_cbranch_scc1 .Lmy_n2_kwr
	ds_write_b128 v0, v[32:35] offset:26112
	s_cmp_lt_u32 s9, 5
	s_cbranch_scc1 .Lmy_n2_kwr
	ds_write_b128 v0, v[36:39] offset:34816
	s_cmp_lt_u32 s9, 6
	s_cbranch_scc1 .Lmy_n2_kwr
	ds_write_b128 v0, v[40:43] offset:43520
	s_cmp_lt_u32 s9, 7
	s_cbranch_scc1 .Lmy_n2_kwr
	ds_write_b128 v0, v[44:47] offset:52224
	s_cmp_lt_u32 s9, 8
	s_cbranch_scc1 .Lmy_n2_kwr
	ds_write_b128 v0, v[48:51] offset:60928
.Lmy_n2_kwr:
	ds_write_b128 v11, v[52:55]
	s_cmp_lt_u32 s8, 2
	s_cbranch_scc1 .Lmy_n2_vwr
	ds_write_b128 v11, v[56:59] offset:64
	s_cmp_lt_u32 s8, 3
	s_cbranch_scc1 .Lmy_n2_vwr
	ds_write_b128 v11, v[60:63] offset:128
	s_cmp_lt_u32 s8, 4
	s_cbranch_scc1 .Lmy_n2_vwr
	ds_write_b128 v11, v[64:67] offset:192
	s_cmp_lt_u32 s8, 5
	s_cbranch_scc1 .Lmy_n2_vwr
	ds_write_b128 v11, v[68:71] offset:256
	s_cmp_lt_u32 s8, 6
	s_cbranch_scc1 .Lmy_n2_vwr
	ds_write_b128 v11, v[72:75] offset:320
	s_cmp_lt_u32 s8, 7
	s_cbranch_scc1 .Lmy_n2_vwr
	ds_write_b128 v11, v[76:79] offset:384
	s_cmp_lt_u32 s8, 8
	s_cbranch_scc1 .Lmy_n2_vwr
	ds_write_b128 v11, v[80:83] offset:448
.Lmy_n2_vwr:
	s_lshl_b32 s2, s0, 2
	v_and_or_b32 v20, s2, 12, v101
	s_lshl_b32 s2, s14, 6
	s_and_b32 s2, s2, 0xfffff000
	v_writelane_b32 v255, s14, 22
	v_add_u32_e32 v189, s2, v104
	v_writelane_b32 v255, s2, 23
	v_add_u32_e32 v2, s20, v189
	v_ashrrev_i32_e32 v3, 31, v2
	v_readlane_b32 s2, v255, 16
	v_lshlrev_b64 v[2:3], 12, v[2:3]
	v_readlane_b32 s3, v255, 17
	v_lshlrev_b32_e32 v0, 8, v20
	v_mov_b32_e32 v93, v1
	v_lshl_add_u64 v[2:3], s[2:3], 0, v[2:3]
	v_lshl_add_u64 v[2:3], v[2:3], 0, v[0:1]
	v_lshl_add_u64 v[2:3], v[2:3], 0, v[92:93]
	s_waitcnt lgkmcnt(0)
	s_barrier
	global_load_dwordx4 v[16:19], v[2:3], off
	global_load_dwordx4 v[12:15], v[2:3], off offset:64
	global_load_dwordx4 v[8:11], v[2:3], off offset:128
	global_load_dwordx4 v[4:7], v[2:3], off offset:192
	v_readlane_b32 s2, v255, 12
	v_lshlrev_b32_e32 v2, 2, v20
	v_mov_b32_e32 v3, v1
	v_readlane_b32 s3, v255, 13
	s_lshl_b64 s[0:1], s[0:1], 15
	v_lshl_add_u64 v[94:95], v[84:85], 0, v[0:1]
	v_lshl_add_u64 v[96:97], s[2:3], 0, v[2:3]
	v_readlane_b32 s2, v255, 14
	s_add_u32 s2, s2, s0
	v_readlane_b32 s0, v255, 15
	s_addc_u32 s3, s0, s1
	v_writelane_b32 v255, s2, 24
	v_lshl_add_u64 v[98:99], v[86:87], 0, v[0:1]
	s_mov_b32 s76, 0
	v_writelane_b32 v255, s3, 25
	v_writelane_b32 v255, s15, 26
	v_writelane_b32 v255, s20, 27
	s_branch .LBB0_398

.LBB0_794:
	v_readlane_b32 s0, v254, 2
	v_readlane_b32 s1, v254, 3
	s_add_i32 s0, s0, 1
	v_writelane_b32 v254, s0, 2
	s_cmp_ge_i32 s0, s1
	s_nop 0
	v_writelane_b32 v254, s1, 3
	s_mov_b64 s[0:1], -1
	s_cbranch_scc1 .LBB0_9
	v_readlane_b32 s2, v254, 2
	s_cmp_lg_u32 s66, 0x100
	s_cbranch_scc1 .Lmy_full_bar
	s_mov_b32 s3, 0x1081830
	s_lshr_b32 s3, s3, s2
	s_bitcmp1_b32 s3, 0
	s_cbranch_scc0 .Lmy_full_bar
	s_waitcnt vmcnt(0) lgkmcnt(0)
	s_mov_b64 s[0:1], 0
	s_barrier
	s_branch .LBB0_9
.Lmy_full_bar:
	v_readlane_b32 s0, v254, 5
	v_readlane_b32 s1, v254, 6
	s_andn2_b64 vcc, exec, s[0:1]
	s_cbranch_vccnz .LBB0_807
	s_waitcnt vmcnt(63) expcnt(7) lgkmcnt(15)
	s_barrier
	s_mov_b64 s[0:1], exec
	v_readlane_b32 s2, v254, 56
	v_readlane_b32 s3, v254, 57
	s_and_b64 s[2:3], s[0:1], s[2:3]
	s_mov_b64 exec, s[2:3]
	s_cbranch_execz .LBB0_806
	buffer_wbl2 sc1
	s_waitcnt vmcnt(0)
	s_load_dwordx2 s[2:3], s[64:65], 0x58
	s_mov_b64 s[4:5], exec
	v_mbcnt_lo_u32_b32 v2, s4, 0
	v_mbcnt_hi_u32_b32 v2, s5, v2
	v_cmp_eq_u32_e32 vcc, 0, v2
	s_waitcnt lgkmcnt(0)
	global_load_dword v0, v1, s[2:3] offset:40
	s_and_saveexec_b64 s[6:7], vcc
	s_cbranch_execz .LBB0_799
	s_bcnt1_i32_b64 s4, s[4:5]
	v_mov_b32_e32 v3, s4
	global_atomic_add v3, v1, v3, s[2:3] offset:32 sc0
